# conv31 waves issue LDS-DMA touch loads over the Q tiles of the following score units (prefetch into L2 or last-level cache); W_o epilogue row sums via LDS reduce plus per-workgroup slots instead of fl
# speedup vs baseline: 1.0620x; 1.0064x over previous
;     __device__ __forceinline__ bool next(int i, Unit& u) const {
;         const int L = i * G + c; if (L >= 512) return false;
;         u.pm = L >> 2; u.pn = L & 3; u.kind = 0;
;         u.A = Aq + (size_t)u.pm * TILE + (size_t)u.pn * 512; u.B = Bm + (size_t)(u.pm >> 5) * bstride_b + (size_t)u.pn * bstride_h; return true;
; __device__ __forceinline__ void conv31_phase(LAS unsigned char* lds, const bf16_t* GLU, bf16_t* SZB, const float* cw, const float* cb, const float* lng, const float* lnb, int G, int c, const int widx) {
;     ...
;         conv31_chunk<0>(lds, red, stats, GLU, SZB, cw, cb, lng, lnb, T0, true, tid);
;         conv31_chunk<1>(lds, red, stats, GLU, SZB, cw, cb, lng, lnb, T0 + 16, true, tid);
;         conv31_chunk<2>(lds, red, stats, GLU, SZB, cw, cb, lng, lnb, T0 + 32, true, tid);
;         conv31_chunk<3>(lds, red, stats, GLU, SZB, cw, cb, lng, lnb, T0 + 48, true, tid);
;         conv31_chunk<0>(lds, red, stats, GLU, SZB, cw, cb, lng, lnb, T0 + 64, true, tid);
;         conv31_chunk<1>(lds, red, stats, GLU, SZB, cw, cb, lng, lnb, T0 + 80, true, tid);
;         conv31_chunk<2>(lds, red, stats, GLU, SZB, cw, cb, lng, lnb, T0 + 96, true, tid);
;         conv31_chunk<3>(lds, red, stats, GLU, SZB, cw, cb, lng, lnb, T0 + 112, false, tid);
.Lc31_nonx:
	s_cmp_lt_u32 s7, 4
	s_cbranch_scc1 .Lc31_notouch
	v_lshrrev_b32_e32 v225, 2, v224
	v_and_b32_e32 v227, 3, v224
	v_lshlrev_b32_e32 v227, 7, v227
	v_lshl_add_u32 v227, v225, 11, v227
	s_sub_u32 s4, s7, 4
	s_lshl_b32 s4, s4, 3
	s_lshr_b32 s5, s87, 6
	s_add_u32 s4, s4, s5
	s_lshr_b32 s5, s4, 4
	s_and_b32 s4, s4, 15
	s_lshl_b32 s4, s4, 15
	s_lshl_b32 s5, s5, 6
	s_lshr_b32 s30, s2, 2
	s_add_u32 s5, s5, s30
	s_lshl_b32 s5, s5, 19
	s_add_u32 s4, s4, s5
	s_and_b32 s30, s2, 3
	s_lshl_b32 s30, s30, 9
	s_add_u32 s4, s4, s30
	s_add_u32 s4, s4, 0x13000000
	s_add_u32 s30, s26, s4
	s_addc_u32 s31, s27, 0
	s_mov_b32 m0, 0x2000
	s_nop 0
	global_load_lds_dword v227, s[30:31]

; #define GRID_SYNC() xcd_barrier(xb, tid_of(widx) == 0)
; __global__ void __launch_bounds__(512, 2) fwd_megakernel(Params p) {
;     ...
;     { SchedOut S{(const char*)HA, (const char*)U, (const char*)WOUT, G, bx}; EpiOut E{SGA, SGB, SGX, MERGED}; gemm_phase(lds, 1024, 1024, 1024, S, E, widx); }
;     GRID_SYNC();
;     { SchedWo S{(const char*)MERGED, (const char*)WO, G, bx}; EpiWo E{x, HA  , ROWSS}; gemm_phase(lds, 1024, 1024, 1024, S, E, widx); }
.LBB0_524:
	s_or_b64 exec, exec, s[4:5]
	s_waitcnt lgkmcnt(0)
	s_barrier
	v_mbcnt_lo_u32_b32 v0, -1, 0
	v_mbcnt_hi_u32_b32 v0, -1, v0
	s_and_b64 vcc, exec, s[0:1]
	v_add_u32_e32 v8, s87, v0
	s_lshl_b32 s98, s2, 11
	s_add_u32 s98, s98, 0x2b00000
	s_add_u32 s100, s26, s98
	s_addc_u32 s101, s27, 0
	v_lshlrev_b32_e32 v244, 2, v8
	v_mov_b32_e32 v240, 0xbf800000
	global_store_dword v244, v240, s[100:101]
	s_nop 0
	v_readfirstlane_b32 s10, v8
	s_cbranch_vccnz .LBB0_558
	s_ashr_i32 s4, s2, 31
	s_lshr_b32 s4, s4, 29
	s_add_i32 s6, s2, s4
	s_and_b32 s4, s6, -8
	s_sub_i32 s8, s2, s4
	s_cmp_gt_i32 s8, -1
	s_cbranch_scc0 .LBB0_527
	s_lshl_b32 s7, s8, 6
	s_cbranch_execz .LBB0_528
	s_branch .LBB0_529

; __device__ __forceinline__ u32x2 pk4(f32x4 v) { u32x2 r; r.x = pk_bf16(v[0], v[1]); r.y = pk_bf16(v[2], v[3]); return r; }
; __device__ __forceinline__ f32x4 unpk4(u32x2 v) { return (f32x4){bf_lo(v.x), bf_hi(v.x), bf_lo(v.y), bf_hi(v.y)}; }
;     __device__ __forceinline__ void operator()(const f32x4 (&acc)[2][2][4][2], const Unit& u, int wr, int wc, int fr, int fq) const {
;         const int w4 = wr * 4 + wc, lane = fq * 16 + fr;
; #pragma unroll
;         for (int ai = 0; ai < 2; ++ai) {
;             f32x4 xv[4][2][2];
; #pragma unroll
;             for (int m = 0; m < 4; ++m)
; #pragma unroll
;                 for (int bj = 0; bj < 2; ++bj)
; #pragma unroll
;                     for (int n = 0; n < 2; ++n)
;                         xv[m][bj][n] = __builtin_nontemporal_load((const f32x4*)(X + (size_t)(u.pm * 256 + ai * 128 + wr * 64 + m * 16 + fr) * 1024 + u.pn * 256 + bj * 128 + wc * 32 + n * 16 + fq * 4));
; #pragma unroll
;             for (int m = 0; m < 4; ++m) {
;                 const int row = u.pm * 256 + ai * 128 + wr * 64 + m * 16 + fr; float ss = 0.f;
; #pragma unroll
;                 for (int bj = 0; bj < 2; ++bj)
; #pragma unroll
;                     for (int n = 0; n < 2; ++n) {
;                         const u32x2 hw = pk4(xv[m][bj][n] + acc[ai][bj][m][n]); const f32x4 h = unpk4(hw);
;                         ((u32x2*)HN)[native_slot(u.pm, u.pn, w4, ai, m, bj, n, lane)] = hw; ss += (h[0] * h[0] + h[1] * h[1]) + (h[2] * h[2] + h[3] * h[3]);
;                     }
;                 ss += __shfl_xor(ss, 16); ss += __shfl_xor(ss, 32);
;                 if (fq == 0) unsafeAtomicAdd(ROWSS + row, ss);
;             }
.LBB0_632:
	s_lshl_b32 s21, s38, 8
	v_add_u32_e32 v192, s21, v183
	s_lshl_b32 s28, s56, 8
	s_ashr_i32 s29, s28, 31
	v_lshl_add_u64 v[190:191], s[28:29], 2, v[184:185]
	v_and_b32_e32 v228, 0x30, v182
	s_bfe_u32 s34, s87, 0x20006
	s_lshl_b32 s34, s34, 7
	v_add_u32_e32 v228, s34, v228
	v_mov_b32_e32 v229, 0
	v_lshl_add_u64 v[230:231], s[28:29], 2, v[228:229]
	v_lshl_add_u64 v[202:203], s[22:23], 0, v[230:231]
	global_load_dwordx4 v[232:235], v[202:203], off
	global_load_dwordx4 v[236:239], v[202:203], off offset:64
	global_load_dwordx4 v[240:243], v[202:203], off offset:512
	global_load_dwordx4 v[244:247], v[202:203], off offset:576
	v_lshl_add_u64 v[248:249], s[24:25], 0, v[230:231]
	v_xor_b32_e32 v222, 16, v201
	v_lshlrev_b32_e32 v222, 2, v222
	v_xor_b32_e32 v223, 32, v201
	v_lshlrev_b32_e32 v223, 2, v223
	s_bfe_u32 s99, s87, 0x20006
	s_lshl_b32 s99, s99, 2
	s_add_u32 s99, s99, 0x20400
	v_lshl_add_u32 v251, v183, 4, s99
	v_mov_b32_e32 v220, v192
	v_ashrrev_i32_e32 v221, 31, v220
	v_lshlrev_b64 v[220:221], 12, v[220:221]
	v_lshl_add_u64 v[202:203], v[190:191], 0, v[220:221]
	global_load_dwordx4 v[204:207], v[202:203], off nt
	global_load_dwordx4 v[208:211], v[202:203], off offset:64 nt
	global_load_dwordx4 v[212:215], v[202:203], off offset:512 nt
	global_load_dwordx4 v[216:219], v[202:203], off offset:576 nt
	v_add_u32_e32 v220, 16, v192
	v_ashrrev_i32_e32 v221, 31, v220
	v_lshlrev_b64 v[220:221], 12, v[220:221]
	v_lshl_add_u64 v[202:203], v[190:191], 0, v[220:221]
	global_load_dwordx4 v[172:175], v[202:203], off nt
	global_load_dwordx4 v[168:171], v[202:203], off offset:64 nt
	global_load_dwordx4 v[164:167], v[202:203], off offset:512 nt
	global_load_dwordx4 v[160:163], v[202:203], off offset:576 nt
	v_add_u32_e32 v220, 32, v192
	v_ashrrev_i32_e32 v221, 31, v220
	v_lshlrev_b64 v[220:221], 12, v[220:221]
	v_lshl_add_u64 v[202:203], v[190:191], 0, v[220:221]
	global_load_dwordx4 v[156:159], v[202:203], off nt
	global_load_dwordx4 v[152:155], v[202:203], off offset:64 nt
	global_load_dwordx4 v[148:151], v[202:203], off offset:512 nt
	global_load_dwordx4 v[144:147], v[202:203], off offset:576 nt
	v_add_u32_e32 v220, 48, v192
	v_ashrrev_i32_e32 v221, 31, v220
	v_lshlrev_b64 v[220:221], 12, v[220:221]
	v_lshl_add_u64 v[202:203], v[190:191], 0, v[220:221]
	global_load_dwordx4 v[140:143], v[202:203], off nt
	global_load_dwordx4 v[136:139], v[202:203], off offset:64 nt
	global_load_dwordx4 v[132:135], v[202:203], off offset:512 nt
	global_load_dwordx4 v[128:131], v[202:203], off offset:576 nt
	s_waitcnt vmcnt(12)
	v_pk_add_f32 v[124:125], v[124:125], v[204:205]
	v_pk_add_f32 v[126:127], v[126:127], v[206:207]
	v_pk_add_f32 v[120:121], v[120:121], v[208:209]
	v_pk_add_f32 v[122:123], v[122:123], v[210:211]
	v_pk_add_f32 v[116:117], v[116:117], v[212:213]
	v_pk_add_f32 v[118:119], v[118:119], v[214:215]
	v_pk_add_f32 v[112:113], v[112:113], v[216:217]
	v_pk_add_f32 v[114:115], v[114:115], v[218:219]
	v_mul_f32_e32 v224, v124, v124
	v_fmac_f32_e32 v224, v125, v125
	v_fmac_f32_e32 v224, v126, v126
	v_fmac_f32_e32 v224, v127, v127
	v_fmac_f32_e32 v224, v120, v120
	v_fmac_f32_e32 v224, v121, v121
	v_fmac_f32_e32 v224, v122, v122
	v_fmac_f32_e32 v224, v123, v123
	v_fmac_f32_e32 v224, v116, v116
	v_fmac_f32_e32 v224, v117, v117
	v_fmac_f32_e32 v224, v118, v118
	v_fmac_f32_e32 v224, v119, v119
	v_fmac_f32_e32 v224, v112, v112
	v_fmac_f32_e32 v224, v113, v113
	v_fmac_f32_e32 v224, v114, v114
	v_fmac_f32_e32 v224, v115, v115
	v_add_u32_e32 v220, 128, v192
	v_ashrrev_i32_e32 v221, 31, v220
	v_lshlrev_b64 v[220:221], 12, v[220:221]
	v_lshl_add_u64 v[202:203], v[190:191], 0, v[220:221]
	global_load_dwordx4 v[204:207], v[202:203], off nt
	global_load_dwordx4 v[208:211], v[202:203], off offset:64 nt
	global_load_dwordx4 v[212:215], v[202:203], off offset:512 nt
	global_load_dwordx4 v[216:219], v[202:203], off offset:576 nt
	ds_bpermute_b32 v250, v222, v224
	s_waitcnt lgkmcnt(0)
	v_add_f32_e32 v224, v224, v250
	ds_bpermute_b32 v250, v223, v224
	s_waitcnt lgkmcnt(0)
	v_add_f32_e32 v224, v224, v250
	s_mov_b64 s[34:35], exec
	s_mov_b64 exec, s[4:5]
	ds_write_b32 v251, v224
	s_mov_b64 exec, s[34:35]
	s_waitcnt vmcnt(12)
	v_pk_add_f32 v[108:109], v[108:109], v[172:173]
	v_pk_add_f32 v[110:111], v[110:111], v[174:175]
	v_pk_add_f32 v[104:105], v[104:105], v[168:169]
	v_pk_add_f32 v[106:107], v[106:107], v[170:171]
	v_pk_add_f32 v[100:101], v[100:101], v[164:165]
	v_pk_add_f32 v[102:103], v[102:103], v[166:167]
	v_pk_add_f32 v[96:97], v[96:97], v[160:161]
	v_pk_add_f32 v[98:99], v[98:99], v[162:163]
	v_mul_f32_e32 v225, v108, v108
	v_fmac_f32_e32 v225, v109, v109
	v_fmac_f32_e32 v225, v110, v110
	v_fmac_f32_e32 v225, v111, v111
	v_fmac_f32_e32 v225, v104, v104
	v_fmac_f32_e32 v225, v105, v105
	v_fmac_f32_e32 v225, v106, v106
	v_fmac_f32_e32 v225, v107, v107
	v_fmac_f32_e32 v225, v100, v100
	v_fmac_f32_e32 v225, v101, v101
	v_fmac_f32_e32 v225, v102, v102
	v_fmac_f32_e32 v225, v103, v103
	v_fmac_f32_e32 v225, v96, v96
	v_fmac_f32_e32 v225, v97, v97
	v_fmac_f32_e32 v225, v98, v98
	v_fmac_f32_e32 v225, v99, v99
	v_add_u32_e32 v220, 144, v192
	v_ashrrev_i32_e32 v221, 31, v220
	v_lshlrev_b64 v[220:221], 12, v[220:221]
	v_lshl_add_u64 v[202:203], v[190:191], 0, v[220:221]
	global_load_dwordx4 v[172:175], v[202:203], off nt
	global_load_dwordx4 v[168:171], v[202:203], off offset:64 nt
	global_load_dwordx4 v[164:167], v[202:203], off offset:512 nt
	global_load_dwordx4 v[160:163], v[202:203], off offset:576 nt
	ds_bpermute_b32 v250, v222, v225
	s_waitcnt lgkmcnt(0)
	v_add_f32_e32 v225, v225, v250
	ds_bpermute_b32 v250, v223, v225
	s_waitcnt lgkmcnt(0)
; __device__ __forceinline__ u32x2 pk4(f32x4 v) { u32x2 r; r.x = pk_bf16(v[0], v[1]); r.y = pk_bf16(v[2], v[3]); return r; }
; __device__ __forceinline__ f32x4 unpk4(u32x2 v) { return (f32x4){bf_lo(v.x), bf_hi(v.x), bf_lo(v.y), bf_hi(v.y)}; }
;     __device__ __forceinline__ void operator()(const f32x4 (&acc)[2][2][4][2], const Unit& u, int wr, int wc, int fr, int fq) const {
;     ...
;             for (int m = 0; m < 4; ++m) {
;                 const int row = u.pm * 256 + ai * 128 + wr * 64 + m * 16 + fr; float ss = 0.f;
; #pragma unroll
;                 for (int bj = 0; bj < 2; ++bj)
; #pragma unroll
;                     for (int n = 0; n < 2; ++n) {
;                         const u32x2 hw = pk4(xv[m][bj][n] + acc[ai][bj][m][n]); const f32x4 h = unpk4(hw);
;                         ((u32x2*)HN)[native_slot(u.pm, u.pn, w4, ai, m, bj, n, lane)] = hw; ss += (h[0] * h[0] + h[1] * h[1]) + (h[2] * h[2] + h[3] * h[3]);
;                     }
;                 ss += __shfl_xor(ss, 16); ss += __shfl_xor(ss, 32);
;                 if (fq == 0) unsafeAtomicAdd(ROWSS + row, ss);
;             }
	v_add_f32_e32 v225, v225, v250
	s_mov_b64 s[34:35], exec
	s_mov_b64 exec, s[4:5]
	ds_write_b32 v251, v225 offset:256
	s_mov_b64 exec, s[34:35]
	s_waitcnt vmcnt(12)
	v_pk_add_f32 v[92:93], v[92:93], v[156:157]
	v_pk_add_f32 v[94:95], v[94:95], v[158:159]
	v_pk_add_f32 v[88:89], v[88:89], v[152:153]
	v_pk_add_f32 v[90:91], v[90:91], v[154:155]
	v_pk_add_f32 v[84:85], v[84:85], v[148:149]
	v_pk_add_f32 v[86:87], v[86:87], v[150:151]
	v_pk_add_f32 v[80:81], v[80:81], v[144:145]
	v_pk_add_f32 v[82:83], v[82:83], v[146:147]
	v_mul_f32_e32 v226, v92, v92
	v_fmac_f32_e32 v226, v93, v93
	v_fmac_f32_e32 v226, v94, v94
	v_fmac_f32_e32 v226, v95, v95
	v_fmac_f32_e32 v226, v88, v88
	v_fmac_f32_e32 v226, v89, v89
	v_fmac_f32_e32 v226, v90, v90
	v_fmac_f32_e32 v226, v91, v91
	v_fmac_f32_e32 v226, v84, v84
	v_fmac_f32_e32 v226, v85, v85
	v_fmac_f32_e32 v226, v86, v86
	v_fmac_f32_e32 v226, v87, v87
	v_fmac_f32_e32 v226, v80, v80
	v_fmac_f32_e32 v226, v81, v81
	v_fmac_f32_e32 v226, v82, v82
	v_fmac_f32_e32 v226, v83, v83
	v_add_u32_e32 v220, 160, v192
	v_ashrrev_i32_e32 v221, 31, v220
	v_lshlrev_b64 v[220:221], 12, v[220:221]
	v_lshl_add_u64 v[202:203], v[190:191], 0, v[220:221]
	global_load_dwordx4 v[156:159], v[202:203], off nt
	global_load_dwordx4 v[152:155], v[202:203], off offset:64 nt
	global_load_dwordx4 v[148:151], v[202:203], off offset:512 nt
	global_load_dwordx4 v[144:147], v[202:203], off offset:576 nt
	ds_bpermute_b32 v250, v222, v226
	s_waitcnt lgkmcnt(0)
	v_add_f32_e32 v226, v226, v250
	ds_bpermute_b32 v250, v223, v226
	s_waitcnt lgkmcnt(0)
	v_add_f32_e32 v226, v226, v250
	s_mov_b64 s[34:35], exec
	s_mov_b64 exec, s[4:5]
	ds_write_b32 v251, v226 offset:512
	s_mov_b64 exec, s[34:35]
	s_waitcnt vmcnt(12)
	v_pk_add_f32 v[76:77], v[76:77], v[140:141]
	v_pk_add_f32 v[78:79], v[78:79], v[142:143]
	v_pk_add_f32 v[72:73], v[72:73], v[136:137]
	v_pk_add_f32 v[74:75], v[74:75], v[138:139]
	v_pk_add_f32 v[68:69], v[68:69], v[132:133]
	v_pk_add_f32 v[70:71], v[70:71], v[134:135]
	v_pk_add_f32 v[64:65], v[64:65], v[128:129]
	v_pk_add_f32 v[66:67], v[66:67], v[130:131]
	v_mul_f32_e32 v227, v76, v76
	v_fmac_f32_e32 v227, v77, v77
	v_fmac_f32_e32 v227, v78, v78
	v_fmac_f32_e32 v227, v79, v79
	v_fmac_f32_e32 v227, v72, v72
	v_fmac_f32_e32 v227, v73, v73
	v_fmac_f32_e32 v227, v74, v74
	v_fmac_f32_e32 v227, v75, v75
	v_fmac_f32_e32 v227, v68, v68
	v_fmac_f32_e32 v227, v69, v69
	v_fmac_f32_e32 v227, v70, v70
	v_fmac_f32_e32 v227, v71, v71
	v_fmac_f32_e32 v227, v64, v64
	v_fmac_f32_e32 v227, v65, v65
	v_fmac_f32_e32 v227, v66, v66
	v_fmac_f32_e32 v227, v67, v67
	v_add_u32_e32 v220, 176, v192
	v_ashrrev_i32_e32 v221, 31, v220
	v_lshlrev_b64 v[220:221], 12, v[220:221]
	v_lshl_add_u64 v[202:203], v[190:191], 0, v[220:221]
	global_load_dwordx4 v[140:143], v[202:203], off nt
	global_load_dwordx4 v[136:139], v[202:203], off offset:64 nt
	global_load_dwordx4 v[132:135], v[202:203], off offset:512 nt
	global_load_dwordx4 v[128:131], v[202:203], off offset:576 nt
	ds_bpermute_b32 v250, v222, v227
	s_waitcnt lgkmcnt(0)
	v_add_f32_e32 v227, v227, v250
	ds_bpermute_b32 v250, v223, v227
	s_waitcnt lgkmcnt(0)
	v_add_f32_e32 v227, v227, v250
	s_mov_b64 s[34:35], exec
	s_mov_b64 exec, s[4:5]
	ds_write_b32 v251, v227 offset:768
	s_mov_b64 exec, s[34:35]
	s_waitcnt vmcnt(12)
	v_pk_add_f32 v[60:61], v[60:61], v[204:205]
	v_pk_add_f32 v[62:63], v[62:63], v[206:207]
	v_pk_add_f32 v[56:57], v[56:57], v[208:209]
	v_pk_add_f32 v[58:59], v[58:59], v[210:211]
	v_pk_add_f32 v[52:53], v[52:53], v[212:213]
	v_pk_add_f32 v[54:55], v[54:55], v[214:215]
	v_pk_add_f32 v[48:49], v[48:49], v[216:217]
	v_pk_add_f32 v[50:51], v[50:51], v[218:219]
	v_mul_f32_e32 v228, v60, v60
	v_fmac_f32_e32 v228, v61, v61
	v_fmac_f32_e32 v228, v62, v62
	v_fmac_f32_e32 v228, v63, v63
	v_fmac_f32_e32 v228, v56, v56
	v_fmac_f32_e32 v228, v57, v57
	v_fmac_f32_e32 v228, v58, v58
	v_fmac_f32_e32 v228, v59, v59
	v_fmac_f32_e32 v228, v52, v52
	v_fmac_f32_e32 v228, v53, v53
	v_fmac_f32_e32 v228, v54, v54
	v_fmac_f32_e32 v228, v55, v55
	v_fmac_f32_e32 v228, v48, v48
	v_fmac_f32_e32 v228, v49, v49
	v_fmac_f32_e32 v228, v50, v50
	v_fmac_f32_e32 v228, v51, v51
	ds_bpermute_b32 v250, v222, v228
	s_waitcnt lgkmcnt(0)
	v_add_f32_e32 v228, v228, v250
	ds_bpermute_b32 v250, v223, v228
	s_waitcnt lgkmcnt(0)
	v_add_f32_e32 v228, v228, v250
	s_mov_b64 s[34:35], exec
	s_mov_b64 exec, s[4:5]
	ds_write_b32 v251, v228 offset:2048
	s_mov_b64 exec, s[34:35]
	s_waitcnt vmcnt(8)
	v_pk_add_f32 v[44:45], v[44:45], v[172:173]
	v_pk_add_f32 v[46:47], v[46:47], v[174:175]
	v_pk_add_f32 v[40:41], v[40:41], v[168:169]
	v_pk_add_f32 v[42:43], v[42:43], v[170:171]
	v_pk_add_f32 v[36:37], v[36:37], v[164:165]
	v_pk_add_f32 v[38:39], v[38:39], v[166:167]
	v_pk_add_f32 v[32:33], v[32:33], v[160:161]
	v_pk_add_f32 v[34:35], v[34:35], v[162:163]
	v_mul_f32_e32 v229, v44, v44
	v_fmac_f32_e32 v229, v45, v45
	v_fmac_f32_e32 v229, v46, v46
	v_fmac_f32_e32 v229, v47, v47
	v_fmac_f32_e32 v229, v40, v40
	v_fmac_f32_e32 v229, v41, v41
	v_fmac_f32_e32 v229, v42, v42
	v_fmac_f32_e32 v229, v43, v43
	v_fmac_f32_e32 v229, v36, v36
	v_fmac_f32_e32 v229, v37, v37
	v_fmac_f32_e32 v229, v38, v38
	v_fmac_f32_e32 v229, v39, v39
	v_fmac_f32_e32 v229, v32, v32
	v_fmac_f32_e32 v229, v33, v33
	v_fmac_f32_e32 v229, v34, v34
	v_fmac_f32_e32 v229, v35, v35
	ds_bpermute_b32 v250, v222, v229
	s_waitcnt lgkmcnt(0)
	v_add_f32_e32 v229, v229, v250
	ds_bpermute_b32 v250, v223, v229
	s_waitcnt lgkmcnt(0)
	v_add_f32_e32 v229, v229, v250
	s_mov_b64 s[34:35], exec
	s_mov_b64 exec, s[4:5]
	ds_write_b32 v251, v229 offset:2304
	s_mov_b64 exec, s[34:35]
	s_waitcnt vmcnt(4)
; __device__ __forceinline__ u32x2 pk4(f32x4 v) { u32x2 r; r.x = pk_bf16(v[0], v[1]); r.y = pk_bf16(v[2], v[3]); return r; }
; __device__ __forceinline__ f32x4 unpk4(u32x2 v) { return (f32x4){bf_lo(v.x), bf_hi(v.x), bf_lo(v.y), bf_hi(v.y)}; }
;     __device__ __forceinline__ void operator()(const f32x4 (&acc)[2][2][4][2], const Unit& u, int wr, int wc, int fr, int fq) const {
;     ...
;             for (int m = 0; m < 4; ++m) {
;                 const int row = u.pm * 256 + ai * 128 + wr * 64 + m * 16 + fr; float ss = 0.f;
; #pragma unroll
;                 for (int bj = 0; bj < 2; ++bj)
; #pragma unroll
;                     for (int n = 0; n < 2; ++n) {
;                         const u32x2 hw = pk4(xv[m][bj][n] + acc[ai][bj][m][n]); const f32x4 h = unpk4(hw);
;                         ((u32x2*)HN)[native_slot(u.pm, u.pn, w4, ai, m, bj, n, lane)] = hw; ss += (h[0] * h[0] + h[1] * h[1]) + (h[2] * h[2] + h[3] * h[3]);
;                     }
;                 ss += __shfl_xor(ss, 16); ss += __shfl_xor(ss, 32);
;                 if (fq == 0) unsafeAtomicAdd(ROWSS + row, ss);
;             }
; __global__ void __launch_bounds__(512, 2) fwd_megakernel(Params p) {
;     ...
; #pragma unroll
;                 for (int m = 0; m < 4; ++m) {
;                     const float rstd = 1.0f / sqrtf(rs[m] * (1.f / 1024.f) + EPS);
	v_pk_add_f32 v[28:29], v[28:29], v[156:157]
	v_pk_add_f32 v[30:31], v[30:31], v[158:159]
	v_pk_add_f32 v[24:25], v[24:25], v[152:153]
	v_pk_add_f32 v[26:27], v[26:27], v[154:155]
	v_pk_add_f32 v[20:21], v[20:21], v[148:149]
	v_pk_add_f32 v[22:23], v[22:23], v[150:151]
	v_pk_add_f32 v[16:17], v[16:17], v[144:145]
	v_pk_add_f32 v[18:19], v[18:19], v[146:147]
	v_mul_f32_e32 v230, v28, v28
	v_fmac_f32_e32 v230, v29, v29
	v_fmac_f32_e32 v230, v30, v30
	v_fmac_f32_e32 v230, v31, v31
	v_fmac_f32_e32 v230, v24, v24
	v_fmac_f32_e32 v230, v25, v25
	v_fmac_f32_e32 v230, v26, v26
	v_fmac_f32_e32 v230, v27, v27
	v_fmac_f32_e32 v230, v20, v20
	v_fmac_f32_e32 v230, v21, v21
	v_fmac_f32_e32 v230, v22, v22
	v_fmac_f32_e32 v230, v23, v23
	v_fmac_f32_e32 v230, v16, v16
	v_fmac_f32_e32 v230, v17, v17
	v_fmac_f32_e32 v230, v18, v18
	v_fmac_f32_e32 v230, v19, v19
	ds_bpermute_b32 v250, v222, v230
	s_waitcnt lgkmcnt(0)
	v_add_f32_e32 v230, v230, v250
	ds_bpermute_b32 v250, v223, v230
	s_waitcnt lgkmcnt(0)
	v_add_f32_e32 v230, v230, v250
	s_mov_b64 s[34:35], exec
	s_mov_b64 exec, s[4:5]
	ds_write_b32 v251, v230 offset:2560
	s_mov_b64 exec, s[34:35]
	s_waitcnt vmcnt(0)
	v_pk_add_f32 v[12:13], v[12:13], v[140:141]
	v_pk_add_f32 v[14:15], v[14:15], v[142:143]
	v_pk_add_f32 v[8:9], v[8:9], v[136:137]
	v_pk_add_f32 v[10:11], v[10:11], v[138:139]
	v_pk_add_f32 v[4:5], v[4:5], v[132:133]
	v_pk_add_f32 v[6:7], v[6:7], v[134:135]
	v_pk_add_f32 v[0:1], v[0:1], v[128:129]
	v_pk_add_f32 v[2:3], v[2:3], v[130:131]
	v_mul_f32_e32 v231, v12, v12
	v_fmac_f32_e32 v231, v13, v13
	v_fmac_f32_e32 v231, v14, v14
	v_fmac_f32_e32 v231, v15, v15
	v_fmac_f32_e32 v231, v8, v8
	v_fmac_f32_e32 v231, v9, v9
	v_fmac_f32_e32 v231, v10, v10
	v_fmac_f32_e32 v231, v11, v11
	v_fmac_f32_e32 v231, v4, v4
	v_fmac_f32_e32 v231, v5, v5
	v_fmac_f32_e32 v231, v6, v6
	v_fmac_f32_e32 v231, v7, v7
	v_fmac_f32_e32 v231, v0, v0
	v_fmac_f32_e32 v231, v1, v1
	v_fmac_f32_e32 v231, v2, v2
	v_fmac_f32_e32 v231, v3, v3
	ds_bpermute_b32 v250, v222, v231
	s_waitcnt lgkmcnt(0)
	v_add_f32_e32 v231, v231, v250
	ds_bpermute_b32 v250, v223, v231
	s_waitcnt lgkmcnt(0)
	v_add_f32_e32 v231, v231, v250
	s_mov_b64 s[34:35], exec
	s_mov_b64 exec, s[4:5]
	ds_write_b32 v251, v231 offset:2816
	s_mov_b64 exec, s[34:35]
	s_waitcnt lgkmcnt(0)
	s_barrier
	s_cmp_ge_u32 s87, 0x100
	s_cbranch_scc1 .Lp5h_wait_0
	v_add_u32_e32 v250, s87, v182
	v_lshlrev_b32_e32 v128, 4, v250
	v_add_u32_e32 v128, 0x20400, v128
	ds_read_b128 v[128:131], v128
	s_lshl_b32 s98, s38, 12
	s_add_u32 s100, s16, 0x100000
	s_addc_u32 s101, s17, 0
	s_add_u32 s100, s100, s98
	s_addc_u32 s101, s101, 0
	v_lshlrev_b32_e32 v136, 4, v250
	s_lshl_b32 s98, s56, 2
	v_add_u32_e32 v137, s98, v136
	s_waitcnt lgkmcnt(0)
	v_add_f32_e32 v128, v128, v129
	v_add_f32_e32 v130, v130, v131
	v_add_f32_e32 v128, v128, v130
	global_store_dword v137, v128, s[100:101] sc0 sc1
	s_mov_b32 s98, 0
.Lp5h_poll_0:
	global_load_dwordx4 v[128:131], v136, s[100:101] sc0 sc1
	s_waitcnt vmcnt(0)
	v_or3_b32 v132, v128, v129, v130
	v_or_b32_e32 v132, v132, v131
	v_cmp_gt_i32_e32 vcc, 0, v132
	s_nop 4
	s_cbranch_vccz .Lp5h_ok_0
	s_add_u32 s98, s98, 1
	s_cmp_lt_u32 s98, 0x8000
	s_cbranch_scc0 .Lp5h_ok_0
	s_sleep 2
	s_branch .Lp5h_poll_0
.Lp5h_ok_0:
	v_add_f32_e32 v128, v128, v129
	v_add_f32_e32 v130, v130, v131
	v_add_f32_e32 v128, v128, v130
	v_lshlrev_b32_e32 v133, 2, v250
	v_add_u32_e32 v133, 0x21400, v133
	ds_write_b32 v133, v128
.Lp5h_wait_0:
	s_waitcnt lgkmcnt(0)
	s_barrier
	v_lshlrev_b32_e32 v250, 2, v183
	v_add_u32_e32 v250, 0x21400, v250
	ds_read_b32 v128, v250 offset:0
	ds_read_b32 v130, v250 offset:64
	ds_read_b32 v132, v250 offset:128
	ds_read_b32 v134, v250 offset:192
	ds_read_b32 v136, v250 offset:512
	ds_read_b32 v138, v250 offset:576
	ds_read_b32 v140, v250 offset:640
	ds_read_b32 v142, v250 offset:704
	v_mov_b32_e32 v144, 0x358637bd
	s_waitcnt lgkmcnt(0)
	v_fmamk_f32 v128, v128, 0x3a800000, v144
	v_fmamk_f32 v130, v130, 0x3a800000, v144
	v_fmamk_f32 v132, v132, 0x3a800000, v144
	v_fmamk_f32 v134, v134, 0x3a800000, v144
	v_fmamk_f32 v136, v136, 0x3a800000, v144
	v_fmamk_f32 v138, v138, 0x3a800000, v144
	v_fmamk_f32 v140, v140, 0x3a800000, v144
	v_fmamk_f32 v142, v142, 0x3a800000, v144
	v_rsq_f32_e32 v146, v128
	v_rsq_f32_e32 v147, v130
	v_rsq_f32_e32 v148, v132
	v_rsq_f32_e32 v149, v134
	v_rsq_f32_e32 v150, v136
	v_rsq_f32_e32 v151, v138
	v_rsq_f32_e32 v152, v140
	v_rsq_f32_e32 v153, v142
	s_nop 0
	v_mul_f32_e32 v154, v128, v146
	v_mul_f32_e32 v155, v130, v147
	v_mul_f32_e32 v156, v132, v148
	v_mul_f32_e32 v157, v134, v149
	v_mul_f32_e32 v158, v136, v150
	v_mul_f32_e32 v159, v138, v151
	v_mul_f32_e32 v160, v140, v152
	v_mul_f32_e32 v161, v142, v153
	v_mul_f32_e32 v154, v154, v146
	v_mul_f32_e32 v155, v155, v147
	v_mul_f32_e32 v156, v156, v148
	v_mul_f32_e32 v157, v157, v149
	v_mul_f32_e32 v158, v158, v150
	v_mul_f32_e32 v159, v159, v151
	v_mul_f32_e32 v160, v160, v152
	v_mul_f32_e32 v161, v161, v153
	v_mov_b32_e32 v144, 0x3fc00000
	v_fma_f32 v154, v154, -0.5, v144
	v_fma_f32 v155, v155, -0.5, v144
	v_fma_f32 v156, v156, -0.5, v144
	v_fma_f32 v157, v157, -0.5, v144
	v_fma_f32 v158, v158, -0.5, v144
	v_fma_f32 v159, v159, -0.5, v144
	v_fma_f32 v160, v160, -0.5, v144
	v_fma_f32 v161, v161, -0.5, v144
	v_mul_f32_e32 v128, v146, v154
	v_mul_f32_e32 v130, v147, v155
	v_mul_f32_e32 v132, v148, v156
	v_mul_f32_e32 v134, v149, v157
	v_mul_f32_e32 v136, v150, v158
	v_mul_f32_e32 v138, v151, v159
	v_mul_f32_e32 v140, v152, v160
	v_mul_f32_e32 v142, v153, v161
	v_mov_b32_e32 v220, v192
	v_ashrrev_i32_e32 v221, 31, v220
	v_lshlrev_b64 v[220:221], 12, v[220:221]
	v_lshl_add_u64 v[202:203], v[248:249], 0, v[220:221]
; __device__ __forceinline__ f32x4 unpk4(u32x2 v) { return (f32x4){bf_lo(v.x), bf_hi(v.x), bf_lo(v.y), bf_hi(v.y)}; }
; __global__ void __launch_bounds__(512, 2) fwd_megakernel(Params p) {
;     ...
;                 for (int m = 0; m < 4; ++m) {
;                     const float rstd = 1.0f / sqrtf(rs[m] * (1.f / 1024.f) + EPS);
; #pragma unroll
;                     for (int bj = 0; bj < 2; ++bj)
; #pragma unroll
;                         for (int n = 0; n < 2; ++n)
;                             *(f32x4*)(p.out + (size_t)(pm * 256 + ai * 128 + wr * 64 + m * 16 + fr) * 1024 + pn * 256 + bj * 128 + wc * 32 + n * 16 + fq * 4) = unpk4(hv[m][bj][n]) * rstd * gg[bj][n];
	v_pk_mul_f32 v[124:125], v[128:129], v[124:125] op_sel_hi:[0,1]
	v_pk_mul_f32 v[126:127], v[128:129], v[126:127] op_sel_hi:[0,1]
	v_pk_mul_f32 v[120:121], v[128:129], v[120:121] op_sel_hi:[0,1]
	v_pk_mul_f32 v[122:123], v[128:129], v[122:123] op_sel_hi:[0,1]
	v_pk_mul_f32 v[116:117], v[128:129], v[116:117] op_sel_hi:[0,1]
	v_pk_mul_f32 v[118:119], v[128:129], v[118:119] op_sel_hi:[0,1]
	v_pk_mul_f32 v[112:113], v[128:129], v[112:113] op_sel_hi:[0,1]
	v_pk_mul_f32 v[114:115], v[128:129], v[114:115] op_sel_hi:[0,1]
	v_pk_mul_f32 v[124:125], v[232:233], v[124:125]
	v_pk_mul_f32 v[126:127], v[234:235], v[126:127]
	v_pk_mul_f32 v[120:121], v[236:237], v[120:121]
	v_pk_mul_f32 v[122:123], v[238:239], v[122:123]
	v_pk_mul_f32 v[116:117], v[240:241], v[116:117]
	v_pk_mul_f32 v[118:119], v[242:243], v[118:119]
	v_pk_mul_f32 v[112:113], v[244:245], v[112:113]
	v_pk_mul_f32 v[114:115], v[246:247], v[114:115]
	s_nop 0
	global_store_dwordx4 v[202:203], v[124:127], off
	global_store_dwordx4 v[202:203], v[120:123], off offset:64
	global_store_dwordx4 v[202:203], v[116:119], off offset:512
	global_store_dwordx4 v[202:203], v[112:115], off offset:576
	v_add_u32_e32 v220, 16, v192
	v_ashrrev_i32_e32 v221, 31, v220
	v_lshlrev_b64 v[220:221], 12, v[220:221]
	v_lshl_add_u64 v[202:203], v[248:249], 0, v[220:221]
	v_pk_mul_f32 v[108:109], v[130:131], v[108:109] op_sel_hi:[0,1]
	v_pk_mul_f32 v[110:111], v[130:131], v[110:111] op_sel_hi:[0,1]
	v_pk_mul_f32 v[104:105], v[130:131], v[104:105] op_sel_hi:[0,1]
	v_pk_mul_f32 v[106:107], v[130:131], v[106:107] op_sel_hi:[0,1]
	v_pk_mul_f32 v[100:101], v[130:131], v[100:101] op_sel_hi:[0,1]
	v_pk_mul_f32 v[102:103], v[130:131], v[102:103] op_sel_hi:[0,1]
	v_pk_mul_f32 v[96:97], v[130:131], v[96:97] op_sel_hi:[0,1]
	v_pk_mul_f32 v[98:99], v[130:131], v[98:99] op_sel_hi:[0,1]
	v_pk_mul_f32 v[108:109], v[232:233], v[108:109]
	v_pk_mul_f32 v[110:111], v[234:235], v[110:111]
	v_pk_mul_f32 v[104:105], v[236:237], v[104:105]
	v_pk_mul_f32 v[106:107], v[238:239], v[106:107]
	v_pk_mul_f32 v[100:101], v[240:241], v[100:101]
	v_pk_mul_f32 v[102:103], v[242:243], v[102:103]
	v_pk_mul_f32 v[96:97], v[244:245], v[96:97]
	v_pk_mul_f32 v[98:99], v[246:247], v[98:99]
	s_nop 0
	global_store_dwordx4 v[202:203], v[108:111], off
	global_store_dwordx4 v[202:203], v[104:107], off offset:64
	global_store_dwordx4 v[202:203], v[100:103], off offset:512
	global_store_dwordx4 v[202:203], v[96:99], off offset:576
	v_add_u32_e32 v220, 32, v192
	v_ashrrev_i32_e32 v221, 31, v220
	v_lshlrev_b64 v[220:221], 12, v[220:221]
	v_lshl_add_u64 v[202:203], v[248:249], 0, v[220:221]
	v_pk_mul_f32 v[92:93], v[132:133], v[92:93] op_sel_hi:[0,1]
	v_pk_mul_f32 v[94:95], v[132:133], v[94:95] op_sel_hi:[0,1]
	v_pk_mul_f32 v[88:89], v[132:133], v[88:89] op_sel_hi:[0,1]
	v_pk_mul_f32 v[90:91], v[132:133], v[90:91] op_sel_hi:[0,1]
	v_pk_mul_f32 v[84:85], v[132:133], v[84:85] op_sel_hi:[0,1]
	v_pk_mul_f32 v[86:87], v[132:133], v[86:87] op_sel_hi:[0,1]
	v_pk_mul_f32 v[80:81], v[132:133], v[80:81] op_sel_hi:[0,1]
	v_pk_mul_f32 v[82:83], v[132:133], v[82:83] op_sel_hi:[0,1]
	v_pk_mul_f32 v[92:93], v[232:233], v[92:93]
	v_pk_mul_f32 v[94:95], v[234:235], v[94:95]
	v_pk_mul_f32 v[88:89], v[236:237], v[88:89]
	v_pk_mul_f32 v[90:91], v[238:239], v[90:91]
	v_pk_mul_f32 v[84:85], v[240:241], v[84:85]
	v_pk_mul_f32 v[86:87], v[242:243], v[86:87]
	v_pk_mul_f32 v[80:81], v[244:245], v[80:81]
	v_pk_mul_f32 v[82:83], v[246:247], v[82:83]
	s_nop 0
	global_store_dwordx4 v[202:203], v[92:95], off
	global_store_dwordx4 v[202:203], v[88:91], off offset:64
	global_store_dwordx4 v[202:203], v[84:87], off offset:512
	global_store_dwordx4 v[202:203], v[80:83], off offset:576
	v_add_u32_e32 v220, 48, v192
	v_ashrrev_i32_e32 v221, 31, v220
	v_lshlrev_b64 v[220:221], 12, v[220:221]
	v_lshl_add_u64 v[202:203], v[248:249], 0, v[220:221]
	v_pk_mul_f32 v[76:77], v[134:135], v[76:77] op_sel_hi:[0,1]
	v_pk_mul_f32 v[78:79], v[134:135], v[78:79] op_sel_hi:[0,1]
	v_pk_mul_f32 v[72:73], v[134:135], v[72:73] op_sel_hi:[0,1]
	v_pk_mul_f32 v[74:75], v[134:135], v[74:75] op_sel_hi:[0,1]
	v_pk_mul_f32 v[68:69], v[134:135], v[68:69] op_sel_hi:[0,1]
	v_pk_mul_f32 v[70:71], v[134:135], v[70:71] op_sel_hi:[0,1]
	v_pk_mul_f32 v[64:65], v[134:135], v[64:65] op_sel_hi:[0,1]
	v_pk_mul_f32 v[66:67], v[134:135], v[66:67] op_sel_hi:[0,1]
	v_pk_mul_f32 v[76:77], v[232:233], v[76:77]
	v_pk_mul_f32 v[78:79], v[234:235], v[78:79]
	v_pk_mul_f32 v[72:73], v[236:237], v[72:73]
	v_pk_mul_f32 v[74:75], v[238:239], v[74:75]
	v_pk_mul_f32 v[68:69], v[240:241], v[68:69]
	v_pk_mul_f32 v[70:71], v[242:243], v[70:71]
	v_pk_mul_f32 v[64:65], v[244:245], v[64:65]
	v_pk_mul_f32 v[66:67], v[246:247], v[66:67]
	s_nop 0
	global_store_dwordx4 v[202:203], v[76:79], off
	global_store_dwordx4 v[202:203], v[72:75], off offset:64
	global_store_dwordx4 v[202:203], v[68:71], off offset:512
	global_store_dwordx4 v[202:203], v[64:67], off offset:576
	v_add_u32_e32 v220, 128, v192
	v_ashrrev_i32_e32 v221, 31, v220
; __device__ __forceinline__ f32x4 unpk4(u32x2 v) { return (f32x4){bf_lo(v.x), bf_hi(v.x), bf_lo(v.y), bf_hi(v.y)}; }
; __global__ void __launch_bounds__(512, 2) fwd_megakernel(Params p) {
;     ...
; #pragma unroll
;                 for (int m = 0; m < 4; ++m) {
;                     const float rstd = 1.0f / sqrtf(rs[m] * (1.f / 1024.f) + EPS);
; #pragma unroll
;                     for (int bj = 0; bj < 2; ++bj)
; #pragma unroll
;                         for (int n = 0; n < 2; ++n)
;                             *(f32x4*)(p.out + (size_t)(pm * 256 + ai * 128 + wr * 64 + m * 16 + fr) * 1024 + pn * 256 + bj * 128 + wc * 32 + n * 16 + fq * 4) = unpk4(hv[m][bj][n]) * rstd * gg[bj][n];
;                 }
	v_lshlrev_b64 v[220:221], 12, v[220:221]
	v_lshl_add_u64 v[202:203], v[248:249], 0, v[220:221]
	v_pk_mul_f32 v[60:61], v[136:137], v[60:61] op_sel_hi:[0,1]
	v_pk_mul_f32 v[62:63], v[136:137], v[62:63] op_sel_hi:[0,1]
	v_pk_mul_f32 v[56:57], v[136:137], v[56:57] op_sel_hi:[0,1]
	v_pk_mul_f32 v[58:59], v[136:137], v[58:59] op_sel_hi:[0,1]
	v_pk_mul_f32 v[52:53], v[136:137], v[52:53] op_sel_hi:[0,1]
	v_pk_mul_f32 v[54:55], v[136:137], v[54:55] op_sel_hi:[0,1]
	v_pk_mul_f32 v[48:49], v[136:137], v[48:49] op_sel_hi:[0,1]
	v_pk_mul_f32 v[50:51], v[136:137], v[50:51] op_sel_hi:[0,1]
	v_pk_mul_f32 v[60:61], v[232:233], v[60:61]
	v_pk_mul_f32 v[62:63], v[234:235], v[62:63]
	v_pk_mul_f32 v[56:57], v[236:237], v[56:57]
	v_pk_mul_f32 v[58:59], v[238:239], v[58:59]
	v_pk_mul_f32 v[52:53], v[240:241], v[52:53]
	v_pk_mul_f32 v[54:55], v[242:243], v[54:55]
	v_pk_mul_f32 v[48:49], v[244:245], v[48:49]
	v_pk_mul_f32 v[50:51], v[246:247], v[50:51]
	s_nop 0
	global_store_dwordx4 v[202:203], v[60:63], off
	global_store_dwordx4 v[202:203], v[56:59], off offset:64
	global_store_dwordx4 v[202:203], v[52:55], off offset:512
	global_store_dwordx4 v[202:203], v[48:51], off offset:576
	v_add_u32_e32 v220, 144, v192
	v_ashrrev_i32_e32 v221, 31, v220
	v_lshlrev_b64 v[220:221], 12, v[220:221]
	v_lshl_add_u64 v[202:203], v[248:249], 0, v[220:221]
	v_pk_mul_f32 v[44:45], v[138:139], v[44:45] op_sel_hi:[0,1]
	v_pk_mul_f32 v[46:47], v[138:139], v[46:47] op_sel_hi:[0,1]
	v_pk_mul_f32 v[40:41], v[138:139], v[40:41] op_sel_hi:[0,1]
	v_pk_mul_f32 v[42:43], v[138:139], v[42:43] op_sel_hi:[0,1]
	v_pk_mul_f32 v[36:37], v[138:139], v[36:37] op_sel_hi:[0,1]
	v_pk_mul_f32 v[38:39], v[138:139], v[38:39] op_sel_hi:[0,1]
	v_pk_mul_f32 v[32:33], v[138:139], v[32:33] op_sel_hi:[0,1]
	v_pk_mul_f32 v[34:35], v[138:139], v[34:35] op_sel_hi:[0,1]
	v_pk_mul_f32 v[44:45], v[232:233], v[44:45]
	v_pk_mul_f32 v[46:47], v[234:235], v[46:47]
	v_pk_mul_f32 v[40:41], v[236:237], v[40:41]
	v_pk_mul_f32 v[42:43], v[238:239], v[42:43]
	v_pk_mul_f32 v[36:37], v[240:241], v[36:37]
	v_pk_mul_f32 v[38:39], v[242:243], v[38:39]
	v_pk_mul_f32 v[32:33], v[244:245], v[32:33]
	v_pk_mul_f32 v[34:35], v[246:247], v[34:35]
	s_nop 0
	global_store_dwordx4 v[202:203], v[44:47], off
	global_store_dwordx4 v[202:203], v[40:43], off offset:64
	global_store_dwordx4 v[202:203], v[36:39], off offset:512
	global_store_dwordx4 v[202:203], v[32:35], off offset:576
	v_add_u32_e32 v220, 160, v192
	v_ashrrev_i32_e32 v221, 31, v220
	v_lshlrev_b64 v[220:221], 12, v[220:221]
	v_lshl_add_u64 v[202:203], v[248:249], 0, v[220:221]
	v_pk_mul_f32 v[28:29], v[140:141], v[28:29] op_sel_hi:[0,1]
	v_pk_mul_f32 v[30:31], v[140:141], v[30:31] op_sel_hi:[0,1]
	v_pk_mul_f32 v[24:25], v[140:141], v[24:25] op_sel_hi:[0,1]
	v_pk_mul_f32 v[26:27], v[140:141], v[26:27] op_sel_hi:[0,1]
	v_pk_mul_f32 v[20:21], v[140:141], v[20:21] op_sel_hi:[0,1]
	v_pk_mul_f32 v[22:23], v[140:141], v[22:23] op_sel_hi:[0,1]
	v_pk_mul_f32 v[16:17], v[140:141], v[16:17] op_sel_hi:[0,1]
	v_pk_mul_f32 v[18:19], v[140:141], v[18:19] op_sel_hi:[0,1]
	v_pk_mul_f32 v[28:29], v[232:233], v[28:29]
	v_pk_mul_f32 v[30:31], v[234:235], v[30:31]
	v_pk_mul_f32 v[24:25], v[236:237], v[24:25]
	v_pk_mul_f32 v[26:27], v[238:239], v[26:27]
	v_pk_mul_f32 v[20:21], v[240:241], v[20:21]
	v_pk_mul_f32 v[22:23], v[242:243], v[22:23]
	v_pk_mul_f32 v[16:17], v[244:245], v[16:17]
	v_pk_mul_f32 v[18:19], v[246:247], v[18:19]
	s_nop 0
	global_store_dwordx4 v[202:203], v[28:31], off
	global_store_dwordx4 v[202:203], v[24:27], off offset:64
	global_store_dwordx4 v[202:203], v[20:23], off offset:512
	global_store_dwordx4 v[202:203], v[16:19], off offset:576
	v_add_u32_e32 v220, 176, v192
	v_ashrrev_i32_e32 v221, 31, v220
	v_lshlrev_b64 v[220:221], 12, v[220:221]
	v_lshl_add_u64 v[202:203], v[248:249], 0, v[220:221]
	v_pk_mul_f32 v[12:13], v[142:143], v[12:13] op_sel_hi:[0,1]
	v_pk_mul_f32 v[14:15], v[142:143], v[14:15] op_sel_hi:[0,1]
	v_pk_mul_f32 v[8:9], v[142:143], v[8:9] op_sel_hi:[0,1]
	v_pk_mul_f32 v[10:11], v[142:143], v[10:11] op_sel_hi:[0,1]
	v_pk_mul_f32 v[4:5], v[142:143], v[4:5] op_sel_hi:[0,1]
	v_pk_mul_f32 v[6:7], v[142:143], v[6:7] op_sel_hi:[0,1]
	v_pk_mul_f32 v[0:1], v[142:143], v[0:1] op_sel_hi:[0,1]
	v_pk_mul_f32 v[2:3], v[142:143], v[2:3] op_sel_hi:[0,1]
	v_pk_mul_f32 v[12:13], v[232:233], v[12:13]
	v_pk_mul_f32 v[14:15], v[234:235], v[14:15]
	v_pk_mul_f32 v[8:9], v[236:237], v[8:9]
	v_pk_mul_f32 v[10:11], v[238:239], v[10:11]
	v_pk_mul_f32 v[4:5], v[240:241], v[4:5]
	v_pk_mul_f32 v[6:7], v[242:243], v[6:7]
	v_pk_mul_f32 v[0:1], v[244:245], v[0:1]
	v_pk_mul_f32 v[2:3], v[246:247], v[2:3]
	s_nop 0
	global_store_dwordx4 v[202:203], v[12:15], off
	global_store_dwordx4 v[202:203], v[8:11], off offset:64
	global_store_dwordx4 v[202:203], v[4:7], off offset:512
	global_store_dwordx4 v[202:203], v[0:3], off offset:576
	s_andn2_b64 vcc, exec, s[18:19]
	s_mov_b64 s[18:19], -1
	s_cbranch_vccnz .LBB0_621
	s_andn2_b64 vcc, exec, s[6:7]
	s_cbranch_vccnz .LBB0_620
	s_barrier
	s_branch .LBB0_620
